# grid barrier: the last-arriving XCD leader bumps every XCD generation word itself (no relay through each XCD leader), -1.4us per barrier vs baseline barrier
# speedup vs baseline: 1.0178x; 1.0039x over previous
; __device__ __forceinline__ unsigned xb_ld(unsigned* p)              { return __hip_atomic_load(p, __ATOMIC_RELAXED, __HIP_MEMORY_SCOPE_AGENT); }
; __device__ __forceinline__ unsigned xb_add(unsigned* p, unsigned v) { return __hip_atomic_fetch_add(p, v, __ATOMIC_RELAXED, __HIP_MEMORY_SCOPE_AGENT); }
; #define XB_SPIN(cond, bar) do { unsigned _sp = 0; while (cond) { __builtin_amdgcn_s_sleep(1); \
;     if ((++_sp & 255u) == 0u) { if (xb_ld(&(bar)[XB_TMO])) break; if (_sp > XB_SPIN_CAP) { atomicAdd(&(bar)[XB_TMO], 1u); break; } } } } while (0)
; __device__ __forceinline__ void xcd_barrier(unsigned* bar, volatile LAS unsigned* st) {
;     ...
;             const unsigned og = xb_add(&bar[XB_TOP], 1u);
;             const unsigned tg = og / nx;
;             if (og + 1u == (tg + 1u) * nx) xb_add(&bar[XB_TOPGEN], 1u);
;             else XB_SPIN(xb_ld(&bar[XB_TOPGEN]) == tg, bar);
;             __builtin_amdgcn_fence(__ATOMIC_ACQUIRE, "agent");
;             xb_add(&bar[XB_XGEN(x)], 1u);
.LBB0_46:
	s_or_b64 exec, exec, s[10:11]
	v_cvt_f32_u32_e32 v4, v0
	s_waitcnt vmcnt(0)
	v_readfirstlane_b32 s4, v3
	v_sub_u32_e32 v3, 0, v0
	s_add_u32 s8, s2, 0x3c03500
	v_rcp_iflag_f32_e32 v4, v4
	v_add_u32_e32 v2, s4, v2
	v_add_u32_e32 v5, 1, v2
	s_addc_u32 s9, s3, 0
	v_mul_f32_e32 v4, 0x4f7ffffe, v4
	v_cvt_u32_f32_e32 v4, v4
	s_mov_b64 s[12:13], -1
	v_mul_lo_u32 v3, v3, v4
	v_mul_hi_u32 v3, v4, v3
	v_add_u32_e32 v3, v4, v3
	v_mul_hi_u32 v3, v2, v3
	v_mul_lo_u32 v4, v3, v0
	v_sub_u32_e32 v2, v2, v4
	v_add_u32_e32 v6, 1, v3
	v_sub_u32_e32 v4, v2, v0
	v_cmp_ge_u32_e32 vcc, v2, v0
	s_nop 1
	v_cndmask_b32_e32 v3, v3, v6, vcc
	v_cndmask_b32_e32 v2, v2, v4, vcc
	v_add_u32_e32 v4, 1, v3
	v_cmp_ge_u32_e32 vcc, v2, v0
	s_nop 1
	v_cndmask_b32_e32 v4, v3, v4, vcc
	v_mul_lo_u32 v2, v0, v4
	v_add_u32_e32 v0, v2, v0
	v_cmp_ne_u32_e32 vcc, v5, v0
	v_mov_b64_e32 v[2:3], s[8:9]
	s_cbranch_vccnz .Lxb_not_last
	v_mov_b32_e32 v8, 1
	v_mov_b32_e32 v7, 0x3c02400
	global_atomic_add v7, v8, s[2:3]
	v_mov_b32_e32 v7, 0x3c02500
	global_atomic_add v7, v8, s[2:3]
	v_mov_b32_e32 v7, 0x3c02600
	global_atomic_add v7, v8, s[2:3]
	v_mov_b32_e32 v7, 0x3c02700
	global_atomic_add v7, v8, s[2:3]
	v_mov_b32_e32 v7, 0x3c02800
	global_atomic_add v7, v8, s[2:3]
	v_mov_b32_e32 v7, 0x3c02900
	global_atomic_add v7, v8, s[2:3]
	v_mov_b32_e32 v7, 0x3c02a00
	global_atomic_add v7, v8, s[2:3]
	v_mov_b32_e32 v7, 0x3c02b00
	global_atomic_add v7, v8, s[2:3]
	v_mov_b32_e32 v7, 0x3c02c00
	global_atomic_add v7, v8, s[2:3]
	v_mov_b32_e32 v7, 0x3c02d00
	global_atomic_add v7, v8, s[2:3]
	v_mov_b32_e32 v7, 0x3c02e00
	global_atomic_add v7, v8, s[2:3]
	v_mov_b32_e32 v7, 0x3c02f00
	global_atomic_add v7, v8, s[2:3]
	v_mov_b32_e32 v7, 0x3c03000
	global_atomic_add v7, v8, s[2:3]
	v_mov_b32_e32 v7, 0x3c03100
	global_atomic_add v7, v8, s[2:3]
	v_mov_b32_e32 v7, 0x3c03200
	global_atomic_add v7, v8, s[2:3]
	v_mov_b32_e32 v7, 0x3c03300
	global_atomic_add v7, v8, s[2:3]
.Lxb_not_last:
	s_and_saveexec_b64 s[10:11], vcc
	s_cbranch_execz .LBB0_58
	global_load_dword v0, v1, s[8:9] sc1
	s_mov_b64 s[16:17], 0
	s_waitcnt vmcnt(0)
	v_cmp_eq_u32_e32 vcc, v0, v4
	s_and_saveexec_b64 s[14:15], vcc
	s_cbranch_execz .LBB0_57
	s_add_u32 s12, s2, 0x3c00200
	s_addc_u32 s13, s3, 0
	s_mov_b32 s4, 1
	s_mov_b64 s[2:3], 0
	s_branch .LBB0_50

; __device__ __forceinline__ unsigned xb_add(unsigned* p, unsigned v) { return __hip_atomic_fetch_add(p, v, __ATOMIC_RELAXED, __HIP_MEMORY_SCOPE_AGENT); }
; __device__ __forceinline__ void xcd_barrier(unsigned* bar, volatile LAS unsigned* st) {
;     ...
;             __builtin_amdgcn_fence(__ATOMIC_ACQUIRE, "agent");
;             xb_add(&bar[XB_XGEN(x)], 1u);
;             asm volatile("s_waitcnt vmcnt(0)" ::: "memory");
.LBB0_60:
	s_or_b64 exec, exec, s[2:3]
	s_mov_b64 s[2:3], exec
	v_mbcnt_lo_u32_b32 v0, s2, 0
	v_mbcnt_hi_u32_b32 v0, s3, v0
	v_cmp_eq_u32_e32 vcc, 0, v0
	s_waitcnt vmcnt(0)
	buffer_inv sc1
	s_and_saveexec_b64 s[8:9], vcc
	s_cbranch_execz .LBB0_62
.LBB0_62:
	s_or_b64 exec, exec, s[8:9]
	s_waitcnt vmcnt(0)
